# G0: the 32 workgroups with two adaLN units skip the weight copy (rebalance); GEMM accumulators via C=0 peel
# baseline (speedup 1.0000x reference)
; #define LAS __attribute__((address_space(3)))
; __device__ __forceinline__ int launder(int x) { asm volatile("" : "+v"(x)); return x; }
; __device__ __forceinline__ int opaque_s(int x) { asm volatile("" : "+s"(x)); return x; }
; __device__ __forceinline__ const float* inp(int i) { const __attribute__((address_space(4))) Args* ka = (const __attribute__((address_space(4))) Args*)__builtin_amdgcn_kernarg_segment_ptr(); return ka->in[opaque_s(i)]; }
; __device__ __forceinline__ bf16* wsb(const Frame& F, size_t off) { return (bf16*)(F.ws + ((size_t)(unsigned)opaque_s((int)(off >> 20)) << 20)); }
;     const int tid = launder(F.tid), lane = tid & 63, wave = __builtin_amdgcn_readfirstlane(tid >> 6), bid = opaque_s(F.bid);
;     if (bid < wg0) return;
;     LAS float* scr = (LAS float*)(F.lds + wave * 16640);
;     const int gw = (bid - wg0) * NWAVES + wave, NGW = (F.G - wg0) * NWAVES;
;     constexpr int I_GU = (D / 64) * (NGU / 64), I_DN = (DFF / 64) * (D / 64), I_IN = (D / 64) * ((INC + 63) / 64), I_OUT = (D / 64) * (D / 64);
;     const float* gu = inp(second ? I_GU2 : I_GU1) + (size_t)layer * D * NGU; const float* dn = inp(second ? I_D2 : I_D1) + (size_t)layer * DFF * D;
;     const float* sq = second ? inp(I_WOUT) + (size_t)layer * D * D : inp(I_WIN) + (size_t)layer * D * INC;
;     bf16* const pGU = wsb(F, second ? WS_WGU2 : WS_WGU1); bf16* const pDN = wsb(F, second ? WS_WD2 : WS_WD1); bf16* const pSQ = wsb(F, second ? WS_WOUT : WS_WIN);
;     const int nsq = second ? I_OUT : I_IN, nsqb = second ? D / 64 : (INC + 63) / 64, Nsq = second ? D : INC;
;     const int it0 = part == 2 || part == 5 ? I_GU : part == 4 ? I_GU / 2 : part == 6 ? I_GU + I_DN : 0;
;     const int it1 = part == 1 || part == 4 ? I_GU : part == 3 ? I_GU / 2 : part == 5 ? I_GU + I_DN : I_GU + I_DN + nsq;
;     ...
;     TrItem tc, tn; f32x4 vc[16], vn[16];
;     int it = it0 + gw;
;     if (it < it1) { TR_DESCRIBE(it, tc); tr_load(tc, vc, lane); }
.LBB0_29:
	v_mov_b32_e32 v1, v0
	s_add_i32 s1, s60, 0xffffffe0
	s_addk_i32 s33, 0xff00
	s_barrier
	s_cmp_lt_i32 s1, 0
	v_readfirstlane_b32 s0, v1
	s_mov_b32 s13, 0
	s_cbranch_scc1 .LBB0_102
	s_ashr_i32 s15, s0, 6
	s_lshl_b32 s0, s1, 3
	s_add_i32 s34, s0, s15
	s_mov_b32 s0, 7
	s_ashr_i32 s1, s0, 31
	s_lshl_b64 s[0:1], s[0:1], 3
	v_readlane_b32 s8, v252, 2
	v_readlane_b32 s9, v252, 3
	s_add_u32 s0, s8, s0
	s_addc_u32 s1, s9, s1
	s_mov_b32 s4, 8
	s_load_dwordx2 s[0:1], s[0:1], 0x0
	s_ashr_i32 s5, s4, 31
	s_lshl_b64 s[4:5], s[4:5], 3
	s_add_u32 s4, s8, s4
	s_addc_u32 s5, s9, s5
	s_mov_b32 s6, 11
	s_load_dwordx2 s[4:5], s[4:5], 0x0
	s_ashr_i32 s7, s6, 31
	s_lshl_b64 s[6:7], s[6:7], 3
	s_add_u32 s6, s8, s6
	s_addc_u32 s7, s9, s7
	s_mov_b32 s12, 14
	s_load_dwordx2 s[6:7], s[6:7], 0x0
	s_lshl_b64 s[8:9], s[12:13], 20
	s_mov_b32 s12, 58
	s_add_u32 s8, s78, s8
	s_addc_u32 s9, s79, s9
	s_lshl_b64 s[10:11], s[12:13], 20
	s_movk_i32 s12, 0x92
	s_add_u32 s10, s78, s10
	s_addc_u32 s11, s79, s11
	s_lshl_b64 s[12:13], s[12:13], 20
	s_add_u32 s12, s78, s12
	s_addc_u32 s13, s79, s13
	s_cmpk_lt_i32 s34, 0x2c20
	s_cselect_b64 s[20:21], -1, 0
	s_cmpk_gt_i32 s34, 0x2c1f
	v_and_b32_e32 v68, 63, v1
	s_cbranch_scc1 .LBB0_35
	s_cmpk_gt_i32 s34, 0x15ff
	s_cbranch_scc0 .LBB0_36
	s_cmpk_gt_u32 s34, 0x20ff
	s_cbranch_scc0 .LBB0_130
	s_add_i32 s14, s34, 0xdf00
	s_and_b32 s16, s14, 0xffff
	s_mulk_i32 s16, 0x702f
	s_lshr_b32 s16, s16, 16
	s_sub_i32 s17, s14, s16
	s_bfe_u32 s17, s17, 0xf0001
	s_add_i32 s17, s17, s16
	s_bfe_u32 s16, s17, 0xa0006
	s_mulk_i32 s16, 0x59
	s_sub_i32 s14, s14, s16
	s_lshl_b32 s14, s14, 6
	s_and_b32 s35, s14, 0xffc0
	s_and_b32 s14, s17, 0xffc0
	s_waitcnt lgkmcnt(0)
	s_mov_b64 s[22:23], s[6:7]
	s_cbranch_execz .LBB0_131
	s_movk_i32 s37, 0x1620
	s_movk_i32 s36, 0x800
	s_mov_b64 s[16:17], s[12:13]
	s_mov_b32 s18, s35
	s_cbranch_execz .LBB0_37
	s_branch .LBB0_38
